# XCD barrier: dropped the now-unread per-XCD release atomic from the leader path
# baseline (speedup 1.0000x reference)
.LBB0_837:
	s_or_b64 exec, exec, s[14:15]
	s_mov_b64 s[14:15], exec
	v_mbcnt_lo_u32_b32 v0, s14, 0
	v_mbcnt_hi_u32_b32 v0, s15, v0
	v_cmp_eq_u32_e32 vcc, 0, v0
	s_waitcnt vmcnt(0)
	buffer_inv sc1
	s_and_saveexec_b64 s[16:17], vcc
	s_cbranch_execz .LBB0_839
	s_bcnt1_i32_b64 s14, s[14:15]
	v_mov_b32_e32 v0, s14
	v_readlane_b32 s14, v253, 58
	v_readlane_b32 s15, v253, 59
	s_nop 4
.LBB0_839:
	s_or_b64 exec, exec, s[16:17]
	s_waitcnt vmcnt(0)

.LBB0_1049:
	s_or_b64 exec, exec, s[6:7]
	s_mov_b64 s[6:7], exec
	v_mbcnt_lo_u32_b32 v0, s6, 0
	v_mbcnt_hi_u32_b32 v0, s7, v0
	v_cmp_eq_u32_e32 vcc, 0, v0
	s_waitcnt vmcnt(0)
	buffer_inv sc1
	s_and_saveexec_b64 s[8:9], vcc
	s_cbranch_execz .LBB0_1051
	s_bcnt1_i32_b64 s6, s[6:7]
	v_mov_b32_e32 v0, s6
	v_readlane_b32 s6, v253, 58
	v_readlane_b32 s7, v253, 59
	s_nop 4
.LBB0_1051:
	s_or_b64 exec, exec, s[8:9]
	s_waitcnt vmcnt(0)

.LBB0_1401:
	s_or_b64 exec, exec, s[6:7]
	s_mov_b64 s[6:7], exec
	v_mbcnt_lo_u32_b32 v0, s6, 0
	v_mbcnt_hi_u32_b32 v0, s7, v0
	v_cmp_eq_u32_e32 vcc, 0, v0
	s_waitcnt vmcnt(0)
	buffer_inv sc1
	s_and_saveexec_b64 s[8:9], vcc
	s_cbranch_execz .LBB0_1403
	s_bcnt1_i32_b64 s6, s[6:7]
	v_mov_b32_e32 v0, s6
	v_readlane_b32 s6, v253, 58
	v_readlane_b32 s7, v253, 59
	s_nop 4
.LBB0_1403:
	s_or_b64 exec, exec, s[8:9]
	s_waitcnt vmcnt(0)
